# kprio4 + closing barrier before each LayerNorm phase moved behind its gamma/beta loads
# baseline (speedup 1.0000x reference)
; __device__ __forceinline__ void xcd_barrier(const XcdBarrier& b) {
;     ...
;     }
;     __syncthreads();
.LBB0_352:
	s_or_b64 exec, exec, s[4:5]
	s_waitcnt lgkmcnt(0)
	s_nop 0

; __device__ __forceinline__ void ln_phase(const float* gam, const float* bet, const float* XIN, float* XFOUT, bf16_t* XB, bf16_t* XL, const bf16_t* HB, const bf16_t* GP, int gw, int ngw, int lane) {
;     f32x4 gq[8], bq[8];
; #pragma unroll
;     for (int j = 0; j < 4; ++j) { const int col = 8 * lane + 512 * j; gq[2 * j] = *(const f32x4*)(gam + col); gq[2 * j + 1] = *(const f32x4*)(gam + col + 4); bq[2 * j] = *(const f32x4*)(bet + col); bq[2 * j + 1] = *(const f32x4*)(bet + col + 4); }
; #pragma unroll
;     for (int j = 0; j < 8; ++j) asm volatile("" : "+v"(gq[j]), "+v"(bq[j]));
;     for (int m0 = gw; m0 < T; m0 += 2 * ngw) {
.LBB0_358:
	s_load_dwordx4 s[12:15], s[6:7], 0x38
	s_ashr_i32 s2, s2, 6
	s_lshl_b32 s18, s92, 11
	v_readlane_b32 s3, v254, 55
	s_add_i32 s8, s2, s3
	s_lshl_b64 s[2:3], s[18:19], 2
	v_lshlrev_b32_e32 v0, 3, v0
	s_waitcnt lgkmcnt(0)
	s_add_u32 s6, s12, s2
	v_and_b32_e32 v174, 0x1f8, v0
	s_addc_u32 s7, s13, s3
	v_lshlrev_b32_e32 v48, 2, v174
	s_add_u32 s2, s14, s2
	v_or_b32_e32 v44, 0x1000, v48
	v_or_b32_e32 v60, 0x1800, v48
	s_addc_u32 s3, s15, s3
	global_load_dwordx4 v[0:3], v48, s[6:7] offset:16
	global_load_dwordx4 v[4:7], v48, s[6:7]
	global_load_dwordx4 v[8:11], v48, s[2:3] offset:16
	global_load_dwordx4 v[12:15], v48, s[2:3]
	global_load_dwordx4 v[16:19], v48, s[6:7] offset:2064
	global_load_dwordx4 v[20:23], v48, s[6:7] offset:2048
	global_load_dwordx4 v[24:27], v48, s[2:3] offset:2064
	global_load_dwordx4 v[28:31], v48, s[2:3] offset:2048
	global_load_dwordx4 v[32:35], v44, s[6:7] offset:16
	global_load_dwordx4 v[36:39], v44, s[6:7]
	global_load_dwordx4 v[40:43], v44, s[2:3] offset:16
	s_nop 0
	global_load_dwordx4 v[44:47], v44, s[2:3]
	s_nop 0
	global_load_dwordx4 v[48:51], v60, s[6:7] offset:16
	global_load_dwordx4 v[52:55], v60, s[6:7]
	global_load_dwordx4 v[56:59], v60, s[2:3]
	s_nop 0
	global_load_dwordx4 v[60:63], v60, s[2:3] offset:16
	s_cmpk_gt_i32 s8, 0x3fff
	s_waitcnt vmcnt(0)
	s_barrier
	s_cbranch_scc1 .LBB0_393
	s_cmp_lg_u64 s[4:5], 0
	s_cselect_b64 s[6:7], -1, 0
	s_branch .LBB0_361

; __device__ __forceinline__ void ln_phase(const float* gam, const float* bet, const float* XIN, float* XFOUT, bf16_t* XB, bf16_t* XL, const bf16_t* HB, const bf16_t* GP, int gw, int ngw, int lane) {
;     f32x4 gq[8], bq[8];
; #pragma unroll
;     for (int j = 0; j < 4; ++j) { const int col = 8 * lane + 512 * j; gq[2 * j] = *(const f32x4*)(gam + col); gq[2 * j + 1] = *(const f32x4*)(gam + col + 4); bq[2 * j] = *(const f32x4*)(bet + col); bq[2 * j + 1] = *(const f32x4*)(bet + col + 4); }
; #pragma unroll
;     for (int j = 0; j < 8; ++j) asm volatile("" : "+v"(gq[j]), "+v"(bq[j]));
;     for (int m0 = gw; m0 < T; m0 += 2 * ngw) {
.LBB0_960:
	s_andn2_b64 vcc, exec, s[2:3]
	s_cbranch_vccnz .LBB0_1013
	v_mov_b32_e32 v0, v238
	s_load_dwordx4 s[8:11], s[4:5], 0x58
	v_readfirstlane_b32 s2, v0
	s_ashr_i32 s2, s2, 6
	v_readlane_b32 s3, v254, 55
	s_lshl_b32 s18, s92, 11
	s_add_i32 s2, s2, s3
	s_lshl_b64 s[4:5], s[18:19], 2
	v_lshlrev_b32_e32 v0, 3, v0
	s_waitcnt lgkmcnt(0)
	s_add_u32 s6, s8, s4
	v_and_b32_e32 v144, 0x1f8, v0
	s_addc_u32 s7, s9, s5
	v_lshlrev_b32_e32 v48, 2, v144
	s_add_u32 s4, s10, s4
	v_or_b32_e32 v44, 0x1000, v48
	v_or_b32_e32 v60, 0x1800, v48
	s_addc_u32 s5, s11, s5
	global_load_dwordx4 v[0:3], v48, s[6:7] offset:16
	global_load_dwordx4 v[4:7], v48, s[6:7]
	global_load_dwordx4 v[8:11], v48, s[4:5] offset:16
	global_load_dwordx4 v[12:15], v48, s[4:5]
	global_load_dwordx4 v[16:19], v48, s[6:7] offset:2064
	global_load_dwordx4 v[20:23], v48, s[6:7] offset:2048
	global_load_dwordx4 v[24:27], v48, s[4:5] offset:2064
	global_load_dwordx4 v[28:31], v48, s[4:5] offset:2048
	global_load_dwordx4 v[32:35], v44, s[6:7] offset:16
	global_load_dwordx4 v[36:39], v44, s[6:7]
	global_load_dwordx4 v[40:43], v44, s[4:5] offset:16
	s_nop 0
	global_load_dwordx4 v[44:47], v44, s[4:5]
	s_nop 0
	global_load_dwordx4 v[48:51], v60, s[6:7] offset:16
	global_load_dwordx4 v[52:55], v60, s[6:7]
	global_load_dwordx4 v[56:59], v60, s[4:5]
	s_nop 0
	global_load_dwordx4 v[60:63], v60, s[4:5] offset:16
	s_cmpk_gt_i32 s2, 0x3fff
	s_waitcnt vmcnt(0)
	s_barrier
	s_cbranch_scc1 .LBB0_963

; __device__ __forceinline__ void ln_phase(const float* gam, const float* bet, const float* XIN, float* XFOUT, bf16_t* XB, bf16_t* XL, const bf16_t* HB, const bf16_t* GP, int gw, int ngw, int lane) {
;     f32x4 gq[8], bq[8];
; #pragma unroll
;     for (int j = 0; j < 4; ++j) { const int col = 8 * lane + 512 * j; gq[2 * j] = *(const f32x4*)(gam + col); gq[2 * j + 1] = *(const f32x4*)(gam + col + 4); bq[2 * j] = *(const f32x4*)(bet + col); bq[2 * j + 1] = *(const f32x4*)(bet + col + 4); }
; #pragma unroll
;     for (int j = 0; j < 8; ++j) asm volatile("" : "+v"(gq[j]), "+v"(bq[j]));
;     for (int m0 = gw; m0 < T; m0 += 2 * ngw) {
.LBB0_1167:
	v_mov_b32_e32 v0, v238
	s_load_dwordx4 s[8:11], s[4:5], 0x130
	v_readfirstlane_b32 s2, v0
	s_ashr_i32 s2, s2, 6
	v_readlane_b32 s3, v254, 55
	s_lshl_b32 s18, s92, 11
	s_add_i32 s4, s2, s3
	s_lshl_b64 s[2:3], s[18:19], 2
	v_lshlrev_b32_e32 v0, 3, v0
	s_waitcnt lgkmcnt(0)
	s_add_u32 s6, s8, s2
	v_and_b32_e32 v166, 0x1f8, v0
	s_addc_u32 s7, s9, s3
	v_lshlrev_b32_e32 v48, 2, v166
	s_add_u32 s2, s10, s2
	v_or_b32_e32 v44, 0x1000, v48
	v_or_b32_e32 v60, 0x1800, v48
	s_addc_u32 s3, s11, s3
	global_load_dwordx4 v[0:3], v48, s[6:7] offset:16
	global_load_dwordx4 v[4:7], v48, s[6:7]
	global_load_dwordx4 v[8:11], v48, s[2:3] offset:16
	global_load_dwordx4 v[12:15], v48, s[2:3]
	global_load_dwordx4 v[16:19], v48, s[6:7] offset:2064
	global_load_dwordx4 v[20:23], v48, s[6:7] offset:2048
	global_load_dwordx4 v[24:27], v48, s[2:3] offset:2064
	global_load_dwordx4 v[28:31], v48, s[2:3] offset:2048
	global_load_dwordx4 v[32:35], v44, s[6:7] offset:16
	global_load_dwordx4 v[36:39], v44, s[6:7]
	global_load_dwordx4 v[40:43], v44, s[2:3] offset:16
	s_nop 0
	global_load_dwordx4 v[44:47], v44, s[2:3]
	s_nop 0
	global_load_dwordx4 v[48:51], v60, s[6:7] offset:16
	global_load_dwordx4 v[52:55], v60, s[6:7]
	global_load_dwordx4 v[56:59], v60, s[2:3]
	s_nop 0
	global_load_dwordx4 v[60:63], v60, s[2:3] offset:16
	s_cmpk_gt_i32 s4, 0x3fff
	s_waitcnt vmcnt(0)
	s_barrier
	s_cbranch_scc1 .LBB0_1202
	s_cmp_lg_u64 s[14:15], 0
	s_cselect_b64 s[6:7], -1, 0
	s_branch .LBB0_1170
